# proj GEMM K-loop: flips deleted, static s_setprio 1 for waves 0-3 instead of 4-7
# speedup vs baseline: 1.0120x; 1.0023x over previous
; #define LAS __attribute__((address_space(3)))
; DI int opaque_tid() { int t = threadIdx.x; asm volatile("" : "+v"(t)); return t; }
; template <class Epi>
; DI void gemm_phase(LAS unsigned char* lds, const Gemm g, const StaticOrder& S, const Epi& E) {
;     const int tid = opaque_tid(), wid = __builtin_amdgcn_readfirstlane(tid >> 6), lane = tid & 63, wr = wid >> 2, wc = wid & 3, fr = lane & 15, fq = lane >> 4;
;     const int K = g.K, nt = K / BK;
;     unsigned voffA[2], voffB[2];
; #pragma unroll
;     for (int i = 0; i < 2; ++i) { int R, C; stage_rc(tid * 16 + i * 8192, R, C); const int Rb = Epi::PERM ? ((R & ~31) + perm32(R & 31)) : R;
;         voffA[i] = (unsigned)(R * g.lda + C) * 2u; voffB[i] = (unsigned)(Rb * g.ldb + C) * 2u; }
;     const size_t kstep = (size_t)(BK * 2);
;     const size_t hstepA = (size_t)HALF * g.lda * 2, hstepB = (size_t)HALF * g.ldb * 2;
;     const size_t tstepA = 2 * hstepA, tstepB = 2 * hstepB;
;     const unsigned ldsw = (unsigned)wid * 1024u;
;     const int aoff = lds_byte(wr * 64 + fr, fq * 8), boff = lds_byte(wc * 32 + fr, fq * 8);
;     ...
;     Unit cur, nxt; int ui = 0;
;     if (!S.next(0, cur)) return;
; template <int PH>
; DI void run_phase(const Params& P, unsigned char* smem) {
;     ...
;     else if constexpr (PH == 1) { pg8::Gemm gm{P_h, P_winT, NTOK, LDP, DM, DM, DM}; S.init(NTOK, LDP, gridDim.x, blockIdx.x); pg8::EpiProj E{P_proj, LDP}; pg8::gemm_phase((LAS unsigned char*)smem, gm, S, E); }
.LBB0_106:
	s_or_b64 exec, exec, s[2:3]
	s_add_u32 s14, s30, 0x3b000000
	s_addc_u32 s15, s31, 0
	v_mov_b32_e32 v9, v215
	s_waitcnt lgkmcnt(0)
	s_barrier
	s_cmpk_gt_i32 s6, 0x1d7f
	v_readfirstlane_b32 s33, v9
	s_cbranch_scc1 .LBB0_118
	s_nop 1
	s_cmpk_ge_u32 s33, 0x100
	s_cbranch_scc1 .Lp1_prio_done
	s_setprio 1
